# XCD barrier: drop unused per-XCD release atomic; leaders leave without waiting for its completion
# speedup vs baseline: 1.0217x; 1.0005x over previous
; __device__ __forceinline__ unsigned xb_add(unsigned* p, unsigned v) { return __hip_atomic_fetch_add(p, v, __ATOMIC_RELAXED, __HIP_MEMORY_SCOPE_AGENT); }
; __device__ __forceinline__ void xcd_barrier(const XcdBarrier& b) {
;     ...
;             xb_add(&bar[XB_XGEN(b.x)], 1u);
;             asm volatile("s_waitcnt vmcnt(0)" ::: "memory");
.LBB0_602:
	s_waitcnt vmcnt(1)
